# v64 + attention per-segment priority (MFMA segment prio 1, softmax 0) instead of static raise of waves 4-7
# speedup vs baseline: 1.0029x; 1.0029x over previous
; template <int D0> __device__ __forceinline__ void pv_one(f32x16& od, int vb, bf16x8 pa0, bf16x8 pa1, bf16x8 pa2, bf16x8 pa3) {
;   const s16x4 l0 = tr_read<v_rd_off(D0, 0, 0)>(vb), h0 = tr_read<v_rd_off(D0, 0, 1)>(vb), l1 = tr_read<v_rd_off(D0, 1, 0)>(vb), h1 = tr_read<v_rd_off(D0, 1, 1)>(vb);
;   const s16x4 l2 = tr_read<v_rd_off(D0, 2, 0)>(vb), h2 = tr_read<v_rd_off(D0, 2, 1)>(vb), l3 = tr_read<v_rd_off(D0, 3, 0)>(vb), h3 = tr_read<v_rd_off(D0, 3, 1)>(vb);
;   asm volatile("s_waitcnt lgkmcnt(0)" ::: "memory"); SBAR();
;     ...
;   od = __builtin_amdgcn_mfma_f32_32x32x16_bf16(pa0, PK(l0, h0), od, 0, 0, 0);
;   od = __builtin_amdgcn_mfma_f32_32x32x16_bf16(pa1, PK(l1, h1), od, 0, 0, 0);
;   od = __builtin_amdgcn_mfma_f32_32x32x16_bf16(pa2, PK(l2, h2), od, 0, 0, 0);
;   od = __builtin_amdgcn_mfma_f32_32x32x16_bf16(pa3, PK(l3, h3), od, 0, 0, 0);
;     ...
; }
; __device__ __forceinline__ void pv_d0(f32x16* o, int vb, bf16x8 pa0, bf16x8 pa1, bf16x8 pa2, bf16x8 pa3) {
;   pv_one<0>(o[0], vb, pa0, pa1, pa2, pa3); pv_one<1>(o[1], vb, pa0, pa1, pa2, pa3); pv_one<2>(o[2], vb, pa0, pa1, pa2, pa3); pv_one<3>(o[3], vb, pa0, pa1, pa2, pa3);
; }
; __device__ __forceinline__ void qkt_c(f32x16& p0, f32x16& p1, const char* Ks, const bf16x8* qr, const f32x16& negm, int r32, int hi) {
; #pragma unroll
;   for (int d0 = 0; d0 < 4; ++d0) { const int cb = (d0 * 16 + hi * 8) * 2;
;     bf16x8 b0 = *reinterpret_cast<const bf16x8*>(Ks + KSWZ(r32, cb));
;     bf16x8 b1 = *reinterpret_cast<const bf16x8*>(Ks + KSWZ(32 + r32, cb));
;     if (d0 == 0) { p0 = __builtin_amdgcn_mfma_f32_32x32x16_bf16(b0, qr[0], negm, 0, 0, 0); p1 = __builtin_amdgcn_mfma_f32_32x32x16_bf16(b1, qr[0], negm, 0, 0, 0); }
;     else { p0 = __builtin_amdgcn_mfma_f32_32x32x16_bf16(b0, qr[d0], p0, 0, 0, 0); p1 = __builtin_amdgcn_mfma_f32_32x32x16_bf16(b1, qr[d0], p1, 0, 0, 0); } }
; }
; template <int R> __device__ __forceinline__ void bias_r(f32x16& p0, f32x16& p1, float dq, float nslope) {
;   constexpr int C0 = (R & 3) + 8 * (R >> 2);
;   float x0, x1, a0 = p0[R], a1 = p1[R];
;   asm("v_sub_f32_e32 %0, %1, %2" : "=v"(x0) : "n"(__builtin_bit_cast(int, (float)C0)), "v"(dq));
;   asm("v_sub_f32_e32 %0, %1, %2" : "=v"(x1) : "n"(__builtin_bit_cast(int, (float)(C0 + 32))), "v"(dq));
;   asm("v_fma_f32 %0, %1, |%2|, %0" : "+v"(a0) : "v"(nslope), "v"(x0));
;   asm("v_fma_f32 %0, %1, |%2|, %0" : "+v"(a1) : "v"(nslope), "v"(x1));
.LBB0_364:
	s_setprio 1
	ds_read_b128 v[114:117], v195 offset:32768
	ds_read_b128 v[212:215], v195 offset:40960
	ds_read_b128 v[216:219], v196 offset:32768
	s_and_b64 vcc, exec, s[14:15]
	s_waitcnt lgkmcnt(2)
	v_mfma_f32_32x32x16_bf16 v[98:113], v[114:117], v[130:133], v[82:97]
	ds_read_b128 v[220:223], v196 offset:40960
	s_waitcnt lgkmcnt(2)
	v_mfma_f32_32x32x16_bf16 v[114:129], v[212:215], v[130:133], v[82:97]
	ds_read_b128 v[212:215], v197 offset:32768
	s_waitcnt lgkmcnt(2)
	v_mfma_f32_32x32x16_bf16 v[98:113], v[216:219], v[134:137], v[98:113]
	ds_read_b128 v[216:219], v197 offset:40960
	s_waitcnt lgkmcnt(2)
	v_mfma_f32_32x32x16_bf16 v[114:129], v[220:223], v[134:137], v[114:129]
	ds_read_b128 v[220:223], v198 offset:32768
	s_waitcnt lgkmcnt(2)
	v_mfma_f32_32x32x16_bf16 v[98:113], v[212:215], v[138:141], v[98:113]
	ds_read_b128 v[212:215], v198 offset:40960
	s_waitcnt lgkmcnt(2)
	v_mfma_f32_32x32x16_bf16 v[114:129], v[216:219], v[138:141], v[114:129]
	s_cbranch_vccnz .Lqk_tail_0
	ds_read_b64_tr_b16 v[204:205], v194 offset:0
	ds_read_b64_tr_b16 v[206:207], v194 offset:0x800
	ds_read_b64_tr_b16 v[208:209], v194 offset:0x1000
	ds_read_b64_tr_b16 v[210:211], v194 offset:0x1800
	s_waitcnt lgkmcnt(5)
	v_mfma_f32_32x32x16_bf16 v[98:113], v[220:223], v[142:145], v[98:113]
	s_waitcnt lgkmcnt(4)
	v_mfma_f32_32x32x16_bf16 v[114:129], v[212:215], v[142:145], v[114:129]
	s_add_i32 s72, s22, s46
	s_cmp_lt_i32 s46, s23
	s_cselect_b32 s14, s72, s39
	s_lshl_b32 s14, s14, 6
	v_cvt_f32_i32_e32 v0, s14
	v_sub_f32_e32 v0, v192, v0
	ds_read_b64_tr_b16 v[212:213], v194 offset:0x2000
	ds_read_b64_tr_b16 v[214:215], v194 offset:0x2800
	ds_read_b64_tr_b16 v[216:217], v194 offset:0x3000
	ds_read_b64_tr_b16 v[218:219], v194 offset:0x3800
	s_waitcnt lgkmcnt(6)
	v_mfma_f32_32x32x16_bf16 v[64:79], v[2:5], v[204:207], v[64:79]
	v_sub_f32_e32 v14, 0, v0
	v_sub_f32_e32 v15, 0x42000000, v0
	v_fma_f32 v98, v81, |v14|, v98
	v_sub_f32_e32 v14, 0x3f800000, v0
	ds_read_b64_tr_b16 v[204:205], v194 offset:0x200
	ds_read_b64_tr_b16 v[206:207], v194 offset:0xa00
	s_waitcnt lgkmcnt(6)
	v_mfma_f32_32x32x16_bf16 v[64:79], v[6:9], v[208:211], v[64:79]
	v_fma_f32 v114, v81, |v15|, v114
	v_sub_f32_e32 v15, 0x42040000, v0
	v_fma_f32 v99, v81, |v14|, v99
	v_sub_f32_e32 v14, 0x40000000, v0
	ds_read_b64_tr_b16 v[208:209], v194 offset:0x1200
	ds_read_b64_tr_b16 v[210:211], v194 offset:0x1a00
	s_waitcnt lgkmcnt(6)
	v_mfma_f32_32x32x16_bf16 v[64:79], v[10:13], v[212:215], v[64:79]
	v_fma_f32 v115, v81, |v15|, v115
	v_sub_f32_e32 v15, 0x42080000, v0
	v_fma_f32 v100, v81, |v14|, v100
	v_sub_f32_e32 v14, 0x40400000, v0
	ds_read_b64_tr_b16 v[212:213], v194 offset:0x2200
	ds_read_b64_tr_b16 v[214:215], v194 offset:0x2a00
	ds_read_b64_tr_b16 v[220:221], v194 offset:0x3200
	ds_read_b64_tr_b16 v[222:223], v194 offset:0x3a00
	s_waitcnt lgkmcnt(8)
	v_mfma_f32_32x32x16_bf16 v[64:79], v[162:165], v[216:219], v[64:79]
	v_fma_f32 v116, v81, |v15|, v116
	v_sub_f32_e32 v15, 0x420c0000, v0
	v_fma_f32 v101, v81, |v14|, v101
	v_sub_f32_e32 v14, 0x41000000, v0
	s_waitcnt lgkmcnt(6)
	v_mfma_f32_32x32x16_bf16 v[48:63], v[2:5], v[204:207], v[48:63]
	v_fma_f32 v117, v81, |v15|, v117
	v_sub_f32_e32 v15, 0x42200000, v0
	v_fma_f32 v102, v81, |v14|, v102
	v_sub_f32_e32 v14, 0x41100000, v0
	ds_read_b64_tr_b16 v[204:205], v194 offset:0x400
	ds_read_b64_tr_b16 v[206:207], v194 offset:0xc00
	s_waitcnt lgkmcnt(6)
	v_mfma_f32_32x32x16_bf16 v[48:63], v[6:9], v[208:211], v[48:63]
	v_fma_f32 v118, v81, |v15|, v118
	v_sub_f32_e32 v15, 0x42240000, v0
	v_fma_f32 v103, v81, |v14|, v103
	v_sub_f32_e32 v14, 0x41200000, v0
	ds_read_b64_tr_b16 v[208:209], v194 offset:0x1400
	ds_read_b64_tr_b16 v[210:211], v194 offset:0x1c00
	s_waitcnt lgkmcnt(6)
	v_mfma_f32_32x32x16_bf16 v[48:63], v[10:13], v[212:215], v[48:63]
	v_fma_f32 v119, v81, |v15|, v119
	v_sub_f32_e32 v15, 0x42280000, v0
	v_fma_f32 v104, v81, |v14|, v104
	v_sub_f32_e32 v14, 0x41300000, v0
	ds_read_b64_tr_b16 v[212:213], v194 offset:0x2400
	ds_read_b64_tr_b16 v[214:215], v194 offset:0x2c00
	ds_read_b64_tr_b16 v[216:217], v194 offset:0x3400
	ds_read_b64_tr_b16 v[218:219], v194 offset:0x3c00
	s_waitcnt lgkmcnt(8)
	v_mfma_f32_32x32x16_bf16 v[48:63], v[162:165], v[220:223], v[48:63]
	v_fma_f32 v120, v81, |v15|, v120
	v_sub_f32_e32 v15, 0x422c0000, v0
	v_fma_f32 v105, v81, |v14|, v105
	v_sub_f32_e32 v14, 0x41800000, v0
	s_waitcnt lgkmcnt(6)
	v_mfma_f32_32x32x16_bf16 v[32:47], v[2:5], v[204:207], v[32:47]
	v_fma_f32 v121, v81, |v15|, v121
	v_sub_f32_e32 v15, 0x42400000, v0
	v_fma_f32 v106, v81, |v14|, v106
	v_sub_f32_e32 v14, 0x41880000, v0
	ds_read_b64_tr_b16 v[204:205], v194 offset:0x600
	ds_read_b64_tr_b16 v[206:207], v194 offset:0xe00
	s_waitcnt lgkmcnt(6)
	v_mfma_f32_32x32x16_bf16 v[32:47], v[6:9], v[208:211], v[32:47]
	v_fma_f32 v122, v81, |v15|, v122
	v_sub_f32_e32 v15, 0x42440000, v0
	v_fma_f32 v107, v81, |v14|, v107
	v_sub_f32_e32 v14, 0x41900000, v0
	ds_read_b64_tr_b16 v[208:209], v194 offset:0x1600
	ds_read_b64_tr_b16 v[210:211], v194 offset:0x1e00
	s_waitcnt lgkmcnt(6)
	v_mfma_f32_32x32x16_bf16 v[32:47], v[10:13], v[212:215], v[32:47]
	v_fma_f32 v123, v81, |v15|, v123
	v_sub_f32_e32 v15, 0x42480000, v0
	v_fma_f32 v108, v81, |v14|, v108
	v_sub_f32_e32 v14, 0x41980000, v0
	ds_read_b64_tr_b16 v[212:213], v194 offset:0x2600
	ds_read_b64_tr_b16 v[214:215], v194 offset:0x2e00
	ds_read_b64_tr_b16 v[220:221], v194 offset:0x3600
	ds_read_b64_tr_b16 v[222:223], v194 offset:0x3e00
	s_waitcnt lgkmcnt(8)
	v_mfma_f32_32x32x16_bf16 v[32:47], v[162:165], v[216:219], v[32:47]
	v_fma_f32 v124, v81, |v15|, v124
	v_sub_f32_e32 v15, 0x424c0000, v0
	v_fma_f32 v109, v81, |v14|, v109
	v_sub_f32_e32 v14, 0x41c00000, v0
	s_waitcnt lgkmcnt(6)
	v_mfma_f32_32x32x16_bf16 v[16:31], v[2:5], v[204:207], v[16:31]
	v_fma_f32 v125, v81, |v15|, v125
	v_sub_f32_e32 v15, 0x42600000, v0
	v_fma_f32 v110, v81, |v14|, v110
	v_sub_f32_e32 v14, 0x41c80000, v0
	s_waitcnt lgkmcnt(4)
	v_mfma_f32_32x32x16_bf16 v[16:31], v[6:9], v[208:211], v[16:31]
	v_fma_f32 v126, v81, |v15|, v126
	v_sub_f32_e32 v15, 0x42640000, v0
	v_fma_f32 v111, v81, |v14|, v111
	v_sub_f32_e32 v14, 0x41d00000, v0
	s_waitcnt lgkmcnt(2)
	v_mfma_f32_32x32x16_bf16 v[16:31], v[10:13], v[212:215], v[16:31]
	v_fma_f32 v127, v81, |v15|, v127
	v_sub_f32_e32 v15, 0x42680000, v0
	v_fma_f32 v112, v81, |v14|, v112
	v_sub_f32_e32 v14, 0x41d80000, v0
	s_waitcnt lgkmcnt(0)
	v_mfma_f32_32x32x16_bf16 v[16:31], v[162:165], v[220:223], v[16:31]
	v_sub_f32_e32 v0, 0x426c0000, v0
	v_fma_f32 v128, v81, |v15|, v128
	v_fma_f32 v113, v81, |v14|, v113
	v_fma_f32 v129, v81, |v0|, v129
	s_setprio 0
	s_barrier
	s_branch .Lafter_bias_0

; template <int R> __device__ __forceinline__ void bias_r(f32x16& p0, f32x16& p1, float dq, float nslope) {
;   constexpr int C0 = (R & 3) + 8 * (R >> 2);
;   float x0, x1, a0 = p0[R], a1 = p1[R];
;   asm("v_sub_f32_e32 %0, %1, %2" : "=v"(x0) : "n"(__builtin_bit_cast(int, (float)C0)), "v"(dq));
;   asm("v_sub_f32_e32 %0, %1, %2" : "=v"(x1) : "n"(__builtin_bit_cast(int, (float)(C0 + 32))), "v"(dq));
;   asm("v_fma_f32 %0, %1, |%2|, %0" : "+v"(a0) : "v"(nslope), "v"(x0));
;   asm("v_fma_f32 %0, %1, |%2|, %0" : "+v"(a1) : "v"(nslope), "v"(x1));
;   p0[R] = a0; p1[R] = a1;
;   if constexpr (R < 15) bias_r<R + 1>(p0, p1, dq, nslope);
; }
.LBB0_366:
	s_add_i32 s72, s22, s46
	s_cmp_lt_i32 s46, s23
	s_cselect_b32 s14, s72, s39
	s_lshl_b32 s14, s14, 6
	v_cvt_f32_i32_e32 v0, s14
	s_setprio 0
	s_barrier
	v_sub_f32_e32 v0, v192, v0
	v_sub_f32_e32 v14, 0, v0
	v_sub_f32_e32 v15, 0x42000000, v0
	s_nop 0
	v_fma_f32 v98, v81, |v14|, v98
	v_sub_f32_e32 v14, 0x3f800000, v0
	v_fma_f32 v114, v81, |v15|, v114
	v_sub_f32_e32 v15, 0x42040000, v0
	s_nop 0
	v_fma_f32 v99, v81, |v14|, v99
	v_sub_f32_e32 v14, 0x40000000, v0
	v_fma_f32 v115, v81, |v15|, v115
	v_sub_f32_e32 v15, 0x42080000, v0
	s_nop 0
	v_fma_f32 v100, v81, |v14|, v100
	v_sub_f32_e32 v14, 0x40400000, v0
	v_fma_f32 v116, v81, |v15|, v116
	v_sub_f32_e32 v15, 0x420c0000, v0
	s_nop 0
	v_fma_f32 v101, v81, |v14|, v101
	v_sub_f32_e32 v14, 0x41000000, v0
	v_fma_f32 v117, v81, |v15|, v117
	v_sub_f32_e32 v15, 0x42200000, v0
	s_nop 0
	v_fma_f32 v102, v81, |v14|, v102
	v_sub_f32_e32 v14, 0x41100000, v0
	v_fma_f32 v118, v81, |v15|, v118
	v_sub_f32_e32 v15, 0x42240000, v0
	s_nop 0
	v_fma_f32 v103, v81, |v14|, v103
	v_sub_f32_e32 v14, 0x41200000, v0
	v_fma_f32 v119, v81, |v15|, v119
	v_sub_f32_e32 v15, 0x42280000, v0
	s_nop 0
	v_fma_f32 v104, v81, |v14|, v104
	v_sub_f32_e32 v14, 0x41300000, v0
	v_fma_f32 v120, v81, |v15|, v120
	v_sub_f32_e32 v15, 0x422c0000, v0
	s_nop 0
	v_fma_f32 v105, v81, |v14|, v105
	v_sub_f32_e32 v14, 0x41800000, v0
	v_fma_f32 v121, v81, |v15|, v121
	v_sub_f32_e32 v15, 0x42400000, v0
	s_nop 0
	v_fma_f32 v106, v81, |v14|, v106
	v_sub_f32_e32 v14, 0x41880000, v0
	v_fma_f32 v122, v81, |v15|, v122
	v_sub_f32_e32 v15, 0x42440000, v0
	s_nop 0
	v_fma_f32 v107, v81, |v14|, v107
	v_sub_f32_e32 v14, 0x41900000, v0
	v_fma_f32 v123, v81, |v15|, v123
	v_sub_f32_e32 v15, 0x42480000, v0
	s_nop 0
	v_fma_f32 v108, v81, |v14|, v108
	v_sub_f32_e32 v14, 0x41980000, v0
	v_fma_f32 v124, v81, |v15|, v124
	v_sub_f32_e32 v15, 0x424c0000, v0
	s_nop 0
	v_fma_f32 v109, v81, |v14|, v109
	v_sub_f32_e32 v14, 0x41c00000, v0
	v_fma_f32 v125, v81, |v15|, v125
	v_sub_f32_e32 v15, 0x42600000, v0
	s_nop 0
	v_fma_f32 v110, v81, |v14|, v110
	v_sub_f32_e32 v14, 0x41c80000, v0
	v_fma_f32 v126, v81, |v15|, v126
	v_sub_f32_e32 v15, 0x42640000, v0
	s_nop 0
	v_fma_f32 v111, v81, |v14|, v111
	v_sub_f32_e32 v14, 0x41d00000, v0
	v_fma_f32 v127, v81, |v15|, v127
	v_sub_f32_e32 v15, 0x42680000, v0
	s_nop 0
	v_fma_f32 v112, v81, |v14|, v112
	v_sub_f32_e32 v14, 0x41d80000, v0
	v_sub_f32_e32 v0, 0x426c0000, v0
	v_fma_f32 v128, v81, |v15|, v128
	s_nop 0
	v_fma_f32 v113, v81, |v14|, v113
	v_fma_f32 v129, v81, |v0|, v129

; template <int D0> __device__ __forceinline__ void pv_one(f32x16& od, int vb, bf16x8 pa0, bf16x8 pa1, bf16x8 pa2, bf16x8 pa3) {
;     ...
;   od = __builtin_amdgcn_mfma_f32_32x32x16_bf16(pa2, PK(l2, h2), od, 0, 0, 0);
;   od = __builtin_amdgcn_mfma_f32_32x32x16_bf16(pa3, PK(l3, h3), od, 0, 0, 0);
;     ...
; }
; __device__ __forceinline__ void pv_d0(f32x16* o, int vb, bf16x8 pa0, bf16x8 pa1, bf16x8 pa2, bf16x8 pa3) {
;   pv_one<0>(o[0], vb, pa0, pa1, pa2, pa3); pv_one<1>(o[1], vb, pa0, pa1, pa2, pa3); pv_one<2>(o[2], vb, pa0, pa1, pa2, pa3); pv_one<3>(o[3], vb, pa0, pa1, pa2, pa3);
; }
; __device__ __forceinline__ void qkt_c(f32x16& p0, f32x16& p1, const char* Ks, const bf16x8* qr, const f32x16& negm, int r32, int hi) {
; #pragma unroll
;   for (int d0 = 0; d0 < 4; ++d0) { const int cb = (d0 * 16 + hi * 8) * 2;
;     bf16x8 b0 = *reinterpret_cast<const bf16x8*>(Ks + KSWZ(r32, cb));
;     bf16x8 b1 = *reinterpret_cast<const bf16x8*>(Ks + KSWZ(32 + r32, cb));
;     if (d0 == 0) { p0 = __builtin_amdgcn_mfma_f32_32x32x16_bf16(b0, qr[0], negm, 0, 0, 0); p1 = __builtin_amdgcn_mfma_f32_32x32x16_bf16(b1, qr[0], negm, 0, 0, 0); }
;     else { p0 = __builtin_amdgcn_mfma_f32_32x32x16_bf16(b0, qr[d0], p0, 0, 0, 0); p1 = __builtin_amdgcn_mfma_f32_32x32x16_bf16(b1, qr[d0], p1, 0, 0, 0); } }
; }
; template <int R> __device__ __forceinline__ void bias_r(f32x16& p0, f32x16& p1, float dq, float nslope) {
;   constexpr int C0 = (R & 3) + 8 * (R >> 2);
;   float x0, x1, a0 = p0[R], a1 = p1[R];
;   asm("v_sub_f32_e32 %0, %1, %2" : "=v"(x0) : "n"(__builtin_bit_cast(int, (float)C0)), "v"(dq));
;   asm("v_sub_f32_e32 %0, %1, %2" : "=v"(x1) : "n"(__builtin_bit_cast(int, (float)(C0 + 32))), "v"(dq));
;   asm("v_fma_f32 %0, %1, |%2|, %0" : "+v"(a0) : "v"(nslope), "v"(x0));
;   asm("v_fma_f32 %0, %1, |%2|, %0" : "+v"(a1) : "v"(nslope), "v"(x1));
;   p0[R] = a0; p1[R] = a1;
;   if constexpr (R < 15) bias_r<R + 1>(p0, p1, dq, nslope);
; }
.LBB0_379:
	s_waitcnt lgkmcnt(0)
	s_barrier
	s_setprio 1
	ds_read_b128 v[114:117], v195 offset:49152
	ds_read_b128 v[212:215], v195 offset:57344
	ds_read_b128 v[216:219], v196 offset:49152
	s_andn2_b64 vcc, exec, s[14:15]
	s_waitcnt lgkmcnt(2)
	v_mfma_f32_32x32x16_bf16 v[98:113], v[114:117], v[130:133], v[82:97]
	ds_read_b128 v[220:223], v196 offset:57344
	s_waitcnt lgkmcnt(2)
	v_mfma_f32_32x32x16_bf16 v[114:129], v[212:215], v[130:133], v[82:97]
	ds_read_b128 v[212:215], v197 offset:49152
	s_waitcnt lgkmcnt(2)
	v_mfma_f32_32x32x16_bf16 v[98:113], v[216:219], v[134:137], v[98:113]
	ds_read_b128 v[216:219], v197 offset:57344
	s_waitcnt lgkmcnt(2)
	v_mfma_f32_32x32x16_bf16 v[114:129], v[220:223], v[134:137], v[114:129]
	ds_read_b128 v[220:223], v198 offset:49152
	s_waitcnt lgkmcnt(2)
	v_mfma_f32_32x32x16_bf16 v[98:113], v[212:215], v[138:141], v[98:113]
	ds_read_b128 v[212:215], v198 offset:57344
	s_waitcnt lgkmcnt(2)
	v_mfma_f32_32x32x16_bf16 v[114:129], v[216:219], v[138:141], v[114:129]
	s_cbranch_vccnz .Lqk_tail_1
	ds_read_b64_tr_b16 v[204:205], v193 offset:0
	ds_read_b64_tr_b16 v[206:207], v193 offset:0x800
	ds_read_b64_tr_b16 v[208:209], v193 offset:0x1000
	ds_read_b64_tr_b16 v[210:211], v193 offset:0x1800
	s_waitcnt lgkmcnt(5)
	v_mfma_f32_32x32x16_bf16 v[98:113], v[220:223], v[142:145], v[98:113]
	s_waitcnt lgkmcnt(4)
	v_mfma_f32_32x32x16_bf16 v[114:129], v[212:215], v[142:145], v[114:129]
	s_add_i32 s46, s47, -1
	s_add_i32 s72, s72, 1
	s_add_i32 s14, s39, -1
	s_cmp_lt_i32 s46, s23
	s_cselect_b32 s14, s72, s14
	s_lshl_b32 s14, s14, 6
	v_cvt_f32_i32_e32 v0, s14
	v_sub_f32_e32 v0, v192, v0
	ds_read_b64_tr_b16 v[212:213], v193 offset:0x2000
	ds_read_b64_tr_b16 v[214:215], v193 offset:0x2800
	ds_read_b64_tr_b16 v[216:217], v193 offset:0x3000
	ds_read_b64_tr_b16 v[218:219], v193 offset:0x3800
	s_waitcnt lgkmcnt(6)
	v_mfma_f32_32x32x16_bf16 v[64:79], v[2:5], v[204:207], v[64:79]
	v_sub_f32_e32 v14, 0, v0
	v_sub_f32_e32 v15, 0x42000000, v0
	v_fma_f32 v98, v81, |v14|, v98
	v_sub_f32_e32 v14, 0x3f800000, v0
	ds_read_b64_tr_b16 v[204:205], v193 offset:0x200
	ds_read_b64_tr_b16 v[206:207], v193 offset:0xa00
	s_waitcnt lgkmcnt(6)
	v_mfma_f32_32x32x16_bf16 v[64:79], v[6:9], v[208:211], v[64:79]
	v_fma_f32 v114, v81, |v15|, v114
	v_sub_f32_e32 v15, 0x42040000, v0
	v_fma_f32 v99, v81, |v14|, v99
	v_sub_f32_e32 v14, 0x40000000, v0
	ds_read_b64_tr_b16 v[208:209], v193 offset:0x1200
	ds_read_b64_tr_b16 v[210:211], v193 offset:0x1a00
	s_waitcnt lgkmcnt(6)
	v_mfma_f32_32x32x16_bf16 v[64:79], v[10:13], v[212:215], v[64:79]
	v_fma_f32 v115, v81, |v15|, v115
	v_sub_f32_e32 v15, 0x42080000, v0
	v_fma_f32 v100, v81, |v14|, v100
	v_sub_f32_e32 v14, 0x40400000, v0
	ds_read_b64_tr_b16 v[212:213], v193 offset:0x2200
	ds_read_b64_tr_b16 v[214:215], v193 offset:0x2a00
	ds_read_b64_tr_b16 v[220:221], v193 offset:0x3200
	ds_read_b64_tr_b16 v[222:223], v193 offset:0x3a00
	s_waitcnt lgkmcnt(8)
	v_mfma_f32_32x32x16_bf16 v[64:79], v[162:165], v[216:219], v[64:79]
	v_fma_f32 v116, v81, |v15|, v116
	v_sub_f32_e32 v15, 0x420c0000, v0
	v_fma_f32 v101, v81, |v14|, v101
	v_sub_f32_e32 v14, 0x41000000, v0
	s_waitcnt lgkmcnt(6)
	v_mfma_f32_32x32x16_bf16 v[48:63], v[2:5], v[204:207], v[48:63]
	v_fma_f32 v117, v81, |v15|, v117
	v_sub_f32_e32 v15, 0x42200000, v0
	v_fma_f32 v102, v81, |v14|, v102
	v_sub_f32_e32 v14, 0x41100000, v0
	ds_read_b64_tr_b16 v[204:205], v193 offset:0x400
	ds_read_b64_tr_b16 v[206:207], v193 offset:0xc00
	s_waitcnt lgkmcnt(6)
	v_mfma_f32_32x32x16_bf16 v[48:63], v[6:9], v[208:211], v[48:63]
	v_fma_f32 v118, v81, |v15|, v118
	v_sub_f32_e32 v15, 0x42240000, v0
	v_fma_f32 v103, v81, |v14|, v103
	v_sub_f32_e32 v14, 0x41200000, v0
	ds_read_b64_tr_b16 v[208:209], v193 offset:0x1400
	ds_read_b64_tr_b16 v[210:211], v193 offset:0x1c00
	s_waitcnt lgkmcnt(6)
	v_mfma_f32_32x32x16_bf16 v[48:63], v[10:13], v[212:215], v[48:63]
	v_fma_f32 v119, v81, |v15|, v119
	v_sub_f32_e32 v15, 0x42280000, v0
	v_fma_f32 v104, v81, |v14|, v104
	v_sub_f32_e32 v14, 0x41300000, v0
	ds_read_b64_tr_b16 v[212:213], v193 offset:0x2400
	ds_read_b64_tr_b16 v[214:215], v193 offset:0x2c00
	ds_read_b64_tr_b16 v[216:217], v193 offset:0x3400
	ds_read_b64_tr_b16 v[218:219], v193 offset:0x3c00
	s_waitcnt lgkmcnt(8)
	v_mfma_f32_32x32x16_bf16 v[48:63], v[162:165], v[220:223], v[48:63]
	v_fma_f32 v120, v81, |v15|, v120
	v_sub_f32_e32 v15, 0x422c0000, v0
	v_fma_f32 v105, v81, |v14|, v105
	v_sub_f32_e32 v14, 0x41800000, v0
	s_waitcnt lgkmcnt(6)
	v_mfma_f32_32x32x16_bf16 v[32:47], v[2:5], v[204:207], v[32:47]
	v_fma_f32 v121, v81, |v15|, v121
	v_sub_f32_e32 v15, 0x42400000, v0
	v_fma_f32 v106, v81, |v14|, v106
	v_sub_f32_e32 v14, 0x41880000, v0
	ds_read_b64_tr_b16 v[204:205], v193 offset:0x600
	ds_read_b64_tr_b16 v[206:207], v193 offset:0xe00
	s_waitcnt lgkmcnt(6)
	v_mfma_f32_32x32x16_bf16 v[32:47], v[6:9], v[208:211], v[32:47]
	v_fma_f32 v122, v81, |v15|, v122
	v_sub_f32_e32 v15, 0x42440000, v0
	v_fma_f32 v107, v81, |v14|, v107
	v_sub_f32_e32 v14, 0x41900000, v0
	ds_read_b64_tr_b16 v[208:209], v193 offset:0x1600
	ds_read_b64_tr_b16 v[210:211], v193 offset:0x1e00
	s_waitcnt lgkmcnt(6)
	v_mfma_f32_32x32x16_bf16 v[32:47], v[10:13], v[212:215], v[32:47]
	v_fma_f32 v123, v81, |v15|, v123
	v_sub_f32_e32 v15, 0x42480000, v0
	v_fma_f32 v108, v81, |v14|, v108
	v_sub_f32_e32 v14, 0x41980000, v0
	ds_read_b64_tr_b16 v[212:213], v193 offset:0x2600
	ds_read_b64_tr_b16 v[214:215], v193 offset:0x2e00
	ds_read_b64_tr_b16 v[220:221], v193 offset:0x3600
	ds_read_b64_tr_b16 v[222:223], v193 offset:0x3e00
	s_waitcnt lgkmcnt(8)
	v_mfma_f32_32x32x16_bf16 v[32:47], v[162:165], v[216:219], v[32:47]
	v_fma_f32 v124, v81, |v15|, v124
	v_sub_f32_e32 v15, 0x424c0000, v0
	v_fma_f32 v109, v81, |v14|, v109
	v_sub_f32_e32 v14, 0x41c00000, v0
	s_waitcnt lgkmcnt(6)
	v_mfma_f32_32x32x16_bf16 v[16:31], v[2:5], v[204:207], v[16:31]
	v_fma_f32 v125, v81, |v15|, v125
	v_sub_f32_e32 v15, 0x42600000, v0
	v_fma_f32 v110, v81, |v14|, v110
	v_sub_f32_e32 v14, 0x41c80000, v0
	s_waitcnt lgkmcnt(4)
	v_mfma_f32_32x32x16_bf16 v[16:31], v[6:9], v[208:211], v[16:31]
	v_fma_f32 v126, v81, |v15|, v126
	v_sub_f32_e32 v15, 0x42640000, v0
	v_fma_f32 v111, v81, |v14|, v111
	v_sub_f32_e32 v14, 0x41d00000, v0
	s_waitcnt lgkmcnt(2)
	v_mfma_f32_32x32x16_bf16 v[16:31], v[10:13], v[212:215], v[16:31]
	v_fma_f32 v127, v81, |v15|, v127
	v_sub_f32_e32 v15, 0x42680000, v0
	v_fma_f32 v112, v81, |v14|, v112
	v_sub_f32_e32 v14, 0x41d80000, v0
	s_waitcnt lgkmcnt(0)
	v_mfma_f32_32x32x16_bf16 v[16:31], v[162:165], v[220:223], v[16:31]
	v_sub_f32_e32 v0, 0x426c0000, v0
	v_fma_f32 v128, v81, |v15|, v128
	v_fma_f32 v113, v81, |v14|, v113
	v_fma_f32 v129, v81, |v0|, v129
	s_setprio 0
	s_barrier
	s_branch .Lafter_bias_1

; template <int R> __device__ __forceinline__ void bias_r(f32x16& p0, f32x16& p1, float dq, float nslope) {
;   constexpr int C0 = (R & 3) + 8 * (R >> 2);
;   float x0, x1, a0 = p0[R], a1 = p1[R];
;   asm("v_sub_f32_e32 %0, %1, %2" : "=v"(x0) : "n"(__builtin_bit_cast(int, (float)C0)), "v"(dq));
;   asm("v_sub_f32_e32 %0, %1, %2" : "=v"(x1) : "n"(__builtin_bit_cast(int, (float)(C0 + 32))), "v"(dq));
;   asm("v_fma_f32 %0, %1, |%2|, %0" : "+v"(a0) : "v"(nslope), "v"(x0));
;   asm("v_fma_f32 %0, %1, |%2|, %0" : "+v"(a1) : "v"(nslope), "v"(x1));
;   p0[R] = a0; p1[R] = a1;
;   if constexpr (R < 15) bias_r<R + 1>(p0, p1, dq, nslope);
; }
.LBB0_381:
	s_add_i32 s46, s47, -1
	s_add_i32 s72, s72, 1
	s_add_i32 s14, s39, -1
	s_cmp_lt_i32 s46, s23
	s_cselect_b32 s14, s72, s14
	s_lshl_b32 s14, s14, 6
	v_cvt_f32_i32_e32 v0, s14
	s_setprio 0
	s_barrier
	v_sub_f32_e32 v0, v192, v0
	v_sub_f32_e32 v14, 0, v0
	v_sub_f32_e32 v15, 0x42000000, v0
	s_nop 0
	v_fma_f32 v98, v81, |v14|, v98
	v_sub_f32_e32 v14, 0x3f800000, v0
	v_fma_f32 v114, v81, |v15|, v114
	v_sub_f32_e32 v15, 0x42040000, v0
	s_nop 0
	v_fma_f32 v99, v81, |v14|, v99
	v_sub_f32_e32 v14, 0x40000000, v0
	v_fma_f32 v115, v81, |v15|, v115
	v_sub_f32_e32 v15, 0x42080000, v0
	s_nop 0
	v_fma_f32 v100, v81, |v14|, v100
	v_sub_f32_e32 v14, 0x40400000, v0
	v_fma_f32 v116, v81, |v15|, v116
	v_sub_f32_e32 v15, 0x420c0000, v0
	s_nop 0
	v_fma_f32 v101, v81, |v14|, v101
	v_sub_f32_e32 v14, 0x41000000, v0
	v_fma_f32 v117, v81, |v15|, v117
	v_sub_f32_e32 v15, 0x42200000, v0
	s_nop 0
	v_fma_f32 v102, v81, |v14|, v102
	v_sub_f32_e32 v14, 0x41100000, v0
	v_fma_f32 v118, v81, |v15|, v118
	v_sub_f32_e32 v15, 0x42240000, v0
	s_nop 0
	v_fma_f32 v103, v81, |v14|, v103
	v_sub_f32_e32 v14, 0x41200000, v0
	v_fma_f32 v119, v81, |v15|, v119
	v_sub_f32_e32 v15, 0x42280000, v0
	s_nop 0
	v_fma_f32 v104, v81, |v14|, v104
	v_sub_f32_e32 v14, 0x41300000, v0
	v_fma_f32 v120, v81, |v15|, v120
	v_sub_f32_e32 v15, 0x422c0000, v0
	s_nop 0
	v_fma_f32 v105, v81, |v14|, v105
	v_sub_f32_e32 v14, 0x41800000, v0
	v_fma_f32 v121, v81, |v15|, v121
	v_sub_f32_e32 v15, 0x42400000, v0
	s_nop 0
	v_fma_f32 v106, v81, |v14|, v106
	v_sub_f32_e32 v14, 0x41880000, v0
	v_fma_f32 v122, v81, |v15|, v122
	v_sub_f32_e32 v15, 0x42440000, v0
	s_nop 0
	v_fma_f32 v107, v81, |v14|, v107
	v_sub_f32_e32 v14, 0x41900000, v0
	v_fma_f32 v123, v81, |v15|, v123
	v_sub_f32_e32 v15, 0x42480000, v0
	s_nop 0
	v_fma_f32 v108, v81, |v14|, v108
	v_sub_f32_e32 v14, 0x41980000, v0
	v_fma_f32 v124, v81, |v15|, v124
	v_sub_f32_e32 v15, 0x424c0000, v0
	s_nop 0
	v_fma_f32 v109, v81, |v14|, v109
	v_sub_f32_e32 v14, 0x41c00000, v0
	v_fma_f32 v125, v81, |v15|, v125
	v_sub_f32_e32 v15, 0x42600000, v0
	s_nop 0
	v_fma_f32 v110, v81, |v14|, v110
	v_sub_f32_e32 v14, 0x41c80000, v0
	v_fma_f32 v126, v81, |v15|, v126
	v_sub_f32_e32 v15, 0x42640000, v0
	s_nop 0
	v_fma_f32 v111, v81, |v14|, v111
	v_sub_f32_e32 v14, 0x41d00000, v0
	v_fma_f32 v127, v81, |v15|, v127
	v_sub_f32_e32 v15, 0x42680000, v0
	s_nop 0
	v_fma_f32 v112, v81, |v14|, v112
	v_sub_f32_e32 v14, 0x41d80000, v0
	v_sub_f32_e32 v0, 0x426c0000, v0
	v_fma_f32 v128, v81, |v15|, v128
	s_nop 0
	v_fma_f32 v113, v81, |v14|, v113
	v_fma_f32 v129, v81, |v0|, v129
